# weight conversion tiles: both 32-row loads of a tile issued together
# baseline (speedup 1.0000x reference)
; __global__ void __launch_bounds__(NTHR) mega(P p0, int ph_lo, int ph_hi) {
;   PX p;
;   *(P*)&p = p0;
;   p.wv = __builtin_amdgcn_readfirstlane((int)(threadIdx.x >> 6));
;   __shared__ __attribute__((aligned(16))) unsigned char smem[SMEM_BYTES];
;   cg::grid_group grid = cg::this_grid();
;   for (int ph = ph_lo; ph < ph_hi; ph++) {
.LBB0_1:
	s_load_dwordx16 s[4:19], s[0:1], 0x0
	v_lshrrev_b32_e32 v2, 20, v0
	v_lshrrev_b32_e32 v0, 10, v0
	v_or_b32_e32 v0, v0, v2
	s_mov_b64 s[84:85], 0x100
	s_waitcnt lgkmcnt(0)
	v_writelane_b32 v252, s4, 3
	s_mov_b64 s[88:89], 0x4230100
	s_mov_b64 s[94:95], 0x4230180
	v_writelane_b32 v252, s5, 4
	v_writelane_b32 v252, s6, 5
	v_writelane_b32 v252, s7, 6
	v_writelane_b32 v252, s8, 7
	v_writelane_b32 v252, s9, 8
	v_writelane_b32 v252, s10, 9
	v_writelane_b32 v252, s11, 10
	v_writelane_b32 v252, s12, 11
	v_writelane_b32 v252, s13, 12
	v_writelane_b32 v252, s14, 13
	v_writelane_b32 v252, s15, 14
	v_writelane_b32 v252, s16, 15
	v_writelane_b32 v252, s17, 16
	v_writelane_b32 v252, s18, 17
	v_writelane_b32 v252, s19, 18
	s_load_dwordx16 s[4:19], s[0:1], 0x40
	s_movk_i32 s81, 0x600
	s_mov_b64 s[92:93], 0x1810100
	s_mov_b64 s[30:31], 0x1890100
	s_mov_b64 s[28:29], 0x1810180
	s_waitcnt lgkmcnt(0)
	v_writelane_b32 v252, s4, 19
	s_mov_b64 s[34:35], 0xc230180
	s_mov_b64 s[52:53], 0x1890180
	v_writelane_b32 v252, s5, 20
	v_writelane_b32 v252, s6, 21
	v_writelane_b32 v252, s7, 22
	v_writelane_b32 v252, s8, 23
	v_writelane_b32 v252, s9, 24
	v_writelane_b32 v252, s10, 25
	v_writelane_b32 v252, s11, 26
	v_writelane_b32 v252, s12, 27
	v_writelane_b32 v252, s13, 28
	v_writelane_b32 v252, s14, 29
	v_writelane_b32 v252, s15, 30
	v_writelane_b32 v252, s16, 31
	v_writelane_b32 v252, s17, 32
	v_writelane_b32 v252, s18, 33
	v_writelane_b32 v252, s19, 34
	s_load_dwordx16 s[4:19], s[0:1], 0x80
	s_mov_b64 s[56:57], 0x30100
	s_mov_b64 s[58:59], 0x180
	s_mov_b64 s[54:55], 0x30180
	s_mov_b64 s[86:87], 0x30080
	s_waitcnt lgkmcnt(0)
	v_writelane_b32 v252, s4, 35
	v_mov_b32_e32 v186, 0.5
	v_mov_b32_e32 v210, 1
	v_writelane_b32 v252, s5, 36
	v_writelane_b32 v252, s6, 37
	v_writelane_b32 v252, s7, 38
	v_writelane_b32 v252, s8, 39
	v_writelane_b32 v252, s9, 40
	v_writelane_b32 v252, s10, 41
	v_writelane_b32 v252, s11, 42
	v_writelane_b32 v252, s12, 43
	v_writelane_b32 v252, s13, 44
	v_writelane_b32 v252, s14, 45
	v_writelane_b32 v252, s15, 46
	v_writelane_b32 v252, s16, 47
	v_writelane_b32 v252, s17, 48
	v_writelane_b32 v252, s18, 49
	v_writelane_b32 v252, s19, 50
	s_load_dwordx16 s[4:19], s[0:1], 0xc0
	v_mov_b32_e32 v212, 0x7f800000
	v_mov_b32_e32 v213, 0x3f80
	v_mov_b32_e32 v214, 0x1800
	s_waitcnt lgkmcnt(0)
	v_writelane_b32 v252, s4, 51
	s_nop 1
	v_writelane_b32 v252, s5, 52
	v_writelane_b32 v252, s6, 53
	v_writelane_b32 v252, s7, 54
	v_writelane_b32 v252, s8, 55
	v_writelane_b32 v252, s9, 56
	v_writelane_b32 v252, s10, 57
	v_writelane_b32 v252, s11, 58
	v_writelane_b32 v252, s12, 59
	v_writelane_b32 v252, s13, 60
	v_writelane_b32 v252, s14, 61
	v_writelane_b32 v253, s17, 0
	v_writelane_b32 v252, s15, 62
	v_writelane_b32 v253, s18, 1
	v_writelane_b32 v252, s16, 63
	v_writelane_b32 v253, s19, 2
	s_load_dwordx16 s[4:19], s[0:1], 0x100
	s_waitcnt lgkmcnt(0)
	v_writelane_b32 v253, s4, 3
	s_nop 1
	v_writelane_b32 v253, s5, 4
	v_writelane_b32 v253, s6, 5
	v_writelane_b32 v253, s7, 6
	v_writelane_b32 v253, s8, 7
	v_writelane_b32 v253, s9, 8
	v_writelane_b32 v253, s10, 9
	v_writelane_b32 v253, s11, 10
	v_writelane_b32 v253, s12, 11
	v_writelane_b32 v253, s13, 12
	v_writelane_b32 v253, s14, 13
	v_writelane_b32 v253, s15, 14
	v_writelane_b32 v253, s16, 15
	v_writelane_b32 v253, s17, 16
	v_writelane_b32 v253, s18, 17
	v_writelane_b32 v253, s19, 18
	s_load_dwordx2 s[96:97], s[0:1], 0x150
	s_load_dwordx4 s[4:7], s[0:1], 0x140
	s_load_dword s83, s[0:1], 0x160
	v_readlane_b32 s8, v252, 0
	s_movk_i32 s16, 0x1b1
	s_waitcnt lgkmcnt(0)
	v_writelane_b32 v253, s4, 19
	s_nop 1
	v_writelane_b32 v253, s5, 20
	v_writelane_b32 v253, s6, 21
	v_writelane_b32 v253, s7, 22
	s_add_u32 s4, s0, 0x160
	s_addc_u32 s5, s1, 0
	s_lshl_b32 s10, s83, 3
	s_and_b32 s9, s2, 0xffffffc0
	s_add_i32 s0, s10, 0x8fff
	s_lshl_b32 s11, s8, 3
	s_add_u32 s12, s96, 0x4230000
	v_writelane_b32 v253, s4, 23
	s_addc_u32 s13, s97, 0
	s_nop 0
	v_writelane_b32 v253, s5, 24
	s_add_u32 s4, s96, 0xf230000
	s_addc_u32 s5, s97, 0
	v_writelane_b32 v253, s4, 25
	s_lshl_b32 s1, s8, 9
	s_nop 0
	v_writelane_b32 v253, s5, 26
	v_writelane_b32 v253, s1, 27
	s_lshl_b32 s1, s83, 9
	s_add_u32 s4, s96, 0x10dd8100
	v_writelane_b32 v253, s1, 28
	s_addc_u32 s5, s97, 0
	v_writelane_b32 v253, s4, 29
	s_mov_b32 s1, 0
	s_cmp_eq_u32 s8, 0
	v_writelane_b32 v253, s5, 30
	v_writelane_b32 v253, s0, 31
	s_cselect_b64 s[4:5], -1, 0
	s_nop 0
	v_writelane_b32 v253, s1, 32
	v_writelane_b32 v253, s4, 33
	s_nop 1
	v_writelane_b32 v253, s5, 34
	s_add_u32 s4, s96, 0x10d48000
	s_addc_u32 s5, s97, 0
	v_writelane_b32 v253, s4, 35
	s_cmpk_lt_i32 s8, 0x24d0
	s_nop 0
	v_writelane_b32 v253, s5, 36
	s_cselect_b64 s[4:5], -1, 0
	v_writelane_b32 v253, s4, 37
	s_nop 1
	v_writelane_b32 v253, s5, 38
	s_add_u32 s4, s96, 0x4110000
	s_addc_u32 s5, s97, 0
	v_writelane_b32 v253, s4, 39
	s_nop 1
	v_writelane_b32 v253, s5, 40
	s_add_u32 s4, s96, 0x3e10000
	s_addc_u32 s5, s97, 0
	v_writelane_b32 v253, s4, 41
	s_nop 1
	v_writelane_b32 v253, s5, 42
	s_add_u32 s4, s96, 0x3b10000
	s_addc_u32 s5, s97, 0
	v_writelane_b32 v253, s4, 43
	s_nop 1
	v_writelane_b32 v253, s5, 44
	s_add_u32 s4, s96, 0x3810000
	s_addc_u32 s5, s97, 0
	v_writelane_b32 v253, s4, 45
	s_nop 1
	v_writelane_b32 v253, s5, 46
	s_add_u32 s4, s96, 0x3010000
	s_addc_u32 s5, s97, 0
	v_writelane_b32 v253, s4, 47
	s_nop 1
	v_writelane_b32 v253, s5, 48
	s_add_u32 s4, s96, 0x10bc8000
	s_addc_u32 s5, s97, 0
	v_writelane_b32 v253, s4, 49
	s_nop 1
	v_writelane_b32 v253, s5, 50
	s_add_u32 s4, s96, 0xffc8000
	s_addc_u32 s5, s97, 0
	v_writelane_b32 v253, s4, 51
	s_nop 1
	v_writelane_b32 v253, s5, 52
	s_add_u32 s4, s96, 0xf3c8000
; __global__ void __launch_bounds__(NTHR) mega(P p0, int ph_lo, int ph_hi) {
;   PX p;
;   *(P*)&p = p0;
;   p.wv = __builtin_amdgcn_readfirstlane((int)(threadIdx.x >> 6));
;   __shared__ __attribute__((aligned(16))) unsigned char smem[SMEM_BYTES];
;   cg::grid_group grid = cg::this_grid();
;   for (int ph = ph_lo; ph < ph_hi; ph++) {
	s_addc_u32 s5, s97, 0
	v_writelane_b32 v253, s4, 53
	s_nop 1
	v_writelane_b32 v253, s5, 54
	s_add_u32 s4, s96, 0x3c000000
	s_addc_u32 s5, s97, 0
	v_writelane_b32 v253, s4, 55
	s_nop 1
	v_writelane_b32 v253, s5, 56
	s_add_u32 s4, s96, 0x3e000000
	s_addc_u32 s5, s97, 0
	s_ashr_i32 s1, s8, 31
	s_lshr_b32 s1, s1, 29
	s_add_i32 s1, s8, s1
	s_ashr_i32 s14, s1, 3
	s_and_b32 s1, s1, -8
	s_lshl_b32 s15, s8, 7
	v_writelane_b32 v253, s4, 57
	s_sub_i32 s7, s8, s1
	s_and_b32 s1, s15, 0xf80
	s_and_b32 s3, s11, 0x7fffff00
	s_lshl_b32 s2, s2, 4
	v_writelane_b32 v253, s5, 58
	s_lshl_b32 s4, s7, 7
	s_bitset1_b32 s1, 15
	s_add_i32 s5, s3, 0xffffe000
	s_and_b32 s82, s2, 0x7ffffc00
	s_add_u32 s2, s96, 0xd230000
	v_writelane_b32 v253, s2, 59
	s_addc_u32 s2, s97, 0
	v_writelane_b32 v253, s2, 60
	s_add_u32 s2, s96, 0x10d48100
	s_addc_u32 s3, s97, 0
	v_writelane_b32 v253, s2, 61
	s_mul_i32 s6, s7, 0x81
	s_nop 0
	v_writelane_b32 v253, s3, 62
	s_add_i32 s2, s10, -1
	v_writelane_b32 v253, s2, 63
	s_add_u32 s2, s96, 0x10d90100
	s_addc_u32 s3, s97, 0
	v_writelane_b32 v254, s2, 0
	s_nop 1
	v_writelane_b32 v254, s3, 1
	s_add_u32 s2, s96, 0x1afd8100
	s_addc_u32 s3, s97, 0
	v_writelane_b32 v254, s2, 2
	s_nop 1
	v_writelane_b32 v254, s3, 3
	s_add_u32 s2, s96, 0x36218100
	s_addc_u32 s3, s97, 0
	v_writelane_b32 v254, s2, 4
	s_nop 1
	v_writelane_b32 v254, s3, 5
	s_add_u32 s2, s96, 0x39818100
	s_addc_u32 s3, s97, 0
	v_writelane_b32 v254, s2, 6
	s_nop 1
	v_writelane_b32 v254, s3, 7
	s_add_u32 s2, s96, 0x2c018100
	s_addc_u32 s3, s97, 0
	v_writelane_b32 v254, s2, 8
	s_nop 1
	v_writelane_b32 v254, s3, 9
	s_add_u32 s2, s96, 0x28a18100
	s_addc_u32 s3, s97, 0
	v_writelane_b32 v254, s2, 10
	s_cmpk_lt_i32 s8, 0xb0
	s_nop 0
	v_writelane_b32 v254, s3, 11
	s_cselect_b64 s[2:3], -1, 0
	v_writelane_b32 v254, s2, 12
	s_nop 1
	v_writelane_b32 v254, s3, 13
	s_add_u32 s2, s96, 0x287d8100
	s_addc_u32 s3, s97, 0
	v_writelane_b32 v254, s2, 14
	s_cmpk_lt_i32 s8, 0xd80
	s_nop 0
	v_writelane_b32 v254, s3, 15
	s_cselect_b64 s[2:3], -1, 0
	v_writelane_b32 v254, s2, 16
	s_cmp_lt_i32 s7, 0
	s_nop 0
	v_writelane_b32 v254, s3, 17
	s_cselect_b64 s[2:3], -1, 0
	v_writelane_b32 v254, s2, 18
	s_nop 1
	v_writelane_b32 v254, s3, 19
	s_and_b64 s[2:3], s[2:3], exec
	s_cselect_b32 s2, s16, 0x1b0
	s_mul_i32 s2, s2, s7
	s_cselect_b32 s4, s6, s4
	s_add_i32 s2, s2, s14
	s_mul_hi_i32 s3, s2, 0x2aaaaaab
	s_lshr_b32 s6, s3, 31
	s_ashr_i32 s3, s3, 5
	s_add_i32 s3, s3, s6
	s_mul_i32 s6, s3, 0xc0
	s_sub_i32 s2, s2, s6
	s_bfe_u32 s6, s2, 0x3001c
	s_add_i32 s6, s2, s6
	v_writelane_b32 v254, s7, 20
	s_sext_i32_i16 s7, s6
	s_and_b32 s6, s6, 0xfff8
	s_sub_i32 s2, s2, s6
	s_lshl_b32 s6, s7, 5
	s_sext_i32_i16 s2, s2
	s_and_b32 s6, s6, 0xffffff00
	s_lshl_b32 s3, s3, 11
	s_lshl_b32 s2, s2, 8
	s_ashr_i32 s7, s6, 31
	s_add_i32 s16, s2, s3
	s_lshl_b64 s[2:3], s[6:7], 12
	s_add_u32 s2, s96, s2
	s_addc_u32 s3, s97, s3
	v_writelane_b32 v254, s2, 21
	s_ashr_i32 s17, s16, 31
	s_nop 0
	v_writelane_b32 v254, s3, 22
	s_lshl_b64 s[2:3], s[16:17], 12
	s_add_u32 s2, s12, s2
	s_addc_u32 s3, s13, s3
	v_writelane_b32 v254, s2, 23
	s_nop 1
	v_writelane_b32 v254, s3, 24
	s_mov_b32 s2, s6
	v_writelane_b32 v254, s2, 25
	s_nop 1
	v_writelane_b32 v254, s3, 26
	s_or_b32 s2, s6, 0x80
	s_ashr_i32 s3, s2, 31
	s_lshl_b64 s[2:3], s[2:3], 12
	s_add_u32 s2, s96, s2
	s_addc_u32 s3, s97, s3
	v_writelane_b32 v254, s2, 27
	s_nop 1
	v_writelane_b32 v254, s3, 28
	s_mov_b32 s2, s16
	v_writelane_b32 v254, s2, 29
	s_nop 1
	v_writelane_b32 v254, s3, 30
	s_or_b32 s2, s16, 0x80
	s_ashr_i32 s3, s2, 31
	s_lshl_b64 s[2:3], s[2:3], 12
	s_add_u32 s2, s12, s2
	v_writelane_b32 v254, s12, 31
	s_addc_u32 s3, s13, s3
	s_cmpk_lt_u32 s83, 0x81
	v_writelane_b32 v254, s13, 32
	v_writelane_b32 v254, s2, 33
	s_nop 1
; __global__ void __launch_bounds__(NTHR) mega(P p0, int ph_lo, int ph_hi) {
;   PX p;
;   *(P*)&p = p0;
;   p.wv = __builtin_amdgcn_readfirstlane((int)(threadIdx.x >> 6));
;   __shared__ __attribute__((aligned(16))) unsigned char smem[SMEM_BYTES];
;   cg::grid_group grid = cg::this_grid();
;   for (int ph = ph_lo; ph < ph_hi; ph++) {
	v_writelane_b32 v254, s3, 34
	s_cselect_b64 s[2:3], -1, 0
	v_writelane_b32 v254, s2, 35
	s_cmpk_gt_u32 s8, 0x7f
	s_nop 0
	v_writelane_b32 v254, s3, 36
	s_cselect_b64 s[2:3], -1, 0
	v_writelane_b32 v254, s2, 37
	s_nop 1
	v_writelane_b32 v254, s3, 38
	v_writelane_b32 v254, s11, 39
	s_add_i32 s2, s11, 0xfffffc00
	v_writelane_b32 v254, s2, 40
	s_add_i32 s2, s10, 0xfffffc00
	v_writelane_b32 v254, s2, 41
	s_add_u32 s2, s96, 0x10d48080
	s_addc_u32 s3, s97, 0
	v_writelane_b32 v254, s2, 42
	s_nop 1
	v_writelane_b32 v254, s3, 43
	s_add_i32 s2, s4, s14
	s_ashr_i32 s3, s2, 31
	s_lshr_b32 s3, s3, 26
	s_add_i32 s3, s2, s3
	s_and_b32 s4, s3, 0xffc0
	s_sub_i32 s2, s2, s4
	s_bfe_i32 s4, s2, 0x80000
	s_bfe_u32 s4, s4, 0x3000c
	s_add_i32 s4, s2, s4
	s_bfe_i32 s6, s4, 0x80000
	s_and_b32 s4, s4, 0xf8
	s_sub_i32 s2, s2, s4
	s_sext_i32_i8 s2, s2
	s_lshl_b32 s3, s3, 5
	s_sext_i32_i16 s6, s6
	s_and_b32 s3, s3, 0xfffff800
	s_lshl_b32 s2, s2, 8
	s_add_i32 s4, s2, s3
	s_lshl_b32 s2, s6, 5
	s_and_b32 s6, s2, 0xffffff00
	s_movk_i32 s2, 0x3ff
	v_and_or_b32 v0, v0, s2, v1
	v_writelane_b32 v254, s14, 44
	v_cmp_eq_u32_e64 s[2:3], 0, v0
	s_cmpk_gt_i32 s8, 0x3ff
	s_cselect_b64 s[12:13], -1, 0
	v_writelane_b32 v254, s2, 45
	v_mov_b32_e32 v1, 0
	s_nop 0
	v_writelane_b32 v254, s3, 46
	v_writelane_b32 v254, s12, 47
	s_and_b64 s[2:3], s[12:13], exec
	s_cselect_b32 s2, s5, s6
	s_cselect_b32 s1, s1, s4
	s_abs_i32 s5, s10
	v_cvt_f32_u32_e32 v0, s5
	v_writelane_b32 v254, s13, 48
	v_writelane_b32 v254, s2, 49
	v_writelane_b32 v254, s1, 50
	v_rcp_iflag_f32_e32 v0, v0
	s_ashr_i32 s1, s0, 31
	s_ashr_i32 s2, s10, 31
	v_writelane_b32 v254, s2, 51
	v_mul_f32_e32 v0, 0x4f7ffffe, v0
	v_cvt_u32_f32_e32 v0, v0
	s_xor_b32 s1, s1, s2
	s_sub_i32 s2, 0, s5
	s_abs_i32 s0, s0
	v_readfirstlane_b32 s3, v0
	s_mul_i32 s2, s2, s3
	s_mul_hi_u32 s2, s3, s2
	v_writelane_b32 v254, s10, 52
	s_add_i32 s2, s3, s2
	v_writelane_b32 v254, s2, 53
	s_mul_hi_u32 s2, s0, s2
	s_mul_i32 s3, s2, s5
	s_sub_i32 s0, s0, s3
	s_add_i32 s3, s2, 1
	s_sub_i32 s4, s0, s5
	s_cmp_ge_u32 s0, s5
	s_cselect_b32 s2, s3, s2
	s_cselect_b32 s0, s4, s0
	s_add_i32 s3, s2, 1
	s_cmp_ge_u32 s0, s5
	s_cselect_b32 s0, s3, s2
	s_xor_b32 s0, s0, s1
	s_sub_i32 s0, s0, s1
	v_writelane_b32 v254, s5, 54
	s_cmp_gt_i32 s0, 0
	v_writelane_b32 v254, s0, 55
	s_cselect_b64 s[0:1], -1, 0
	v_writelane_b32 v254, s0, 56
	s_add_i32 s33, s82, 0x10000
	v_mbcnt_lo_u32_b32 v0, -1, 0
	v_writelane_b32 v254, s1, 57
	s_add_i32 s0, s8, 0xfffff000
	v_writelane_b32 v254, s0, 58
	s_lshl_b32 s0, s8, 6
	v_writelane_b32 v254, s0, 59
	s_lshl_b32 s0, s83, 6
	v_writelane_b32 v254, s0, 60
	s_add_i32 s0, s8, 0xe000
	v_writelane_b32 v254, s0, 61
	s_add_i32 s0, s8, 0xffffc7e0
	v_writelane_b32 v254, s0, 62
	s_add_i32 s0, s8, 0xffffc3e0
	v_writelane_b32 v254, s0, 63
	s_add_i32 s0, s8, 0xffffc260
	v_writelane_b32 v255, s0, 0
	s_add_i32 s0, s8, 0xffffc0e0
	v_writelane_b32 v255, s0, 1
	s_add_i32 s0, s8, 0x60
	v_writelane_b32 v255, s0, 2
	v_writelane_b32 v255, s15, 3
	s_add_i32 s1, s15, 0xffffc000
	s_lshl_b32 s0, s83, 7
	v_writelane_b32 v255, s1, 4
	v_writelane_b32 v255, s0, 5
	s_addk_i32 s0, 0xc000
	v_writelane_b32 v255, s0, 6
	v_mbcnt_hi_u32_b32 v211, -1, v0
	v_writelane_b32 v255, s9, 7
	s_add_i32 s64, s82, 0x12000
	s_add_i32 s65, s82, 0x14000
	s_add_i32 s66, s82, 0x16000
	s_add_i32 s67, s82, 0x4000
	s_add_i32 s72, s82, 0x6000
	s_add_i32 s90, s82, 0x18000
	s_add_i32 s91, s82, 0x1a000
	s_add_i32 s78, s82, 0xa000
	s_add_i32 s79, s82, 0x1c000
	s_add_i32 s80, s82, 0x1e000
	v_add_u32_e32 v188, s9, v211
	s_mov_b32 s0, 0
	v_writelane_b32 v255, s0, 60
	v_writelane_b32 v255, s0, 61
	v_writelane_b32 v255, s0, 62
	v_readlane_b32 s0, v252, 1
	v_writelane_b32 v255, s83, 8
	v_readlane_b32 s1, v252, 2
	s_branch .LBB0_6

; #define TIDX(p) ((p).wv * 64 + (int)__builtin_amdgcn_mbcnt_hi(~0u, __builtin_amdgcn_mbcnt_lo(~0u, 0u)))
; DI void gbar(const PX& p, unsigned target) {
;   asm volatile("s_waitcnt vmcnt(0)" ::: "memory");
;   __syncthreads();
;   if (TIDX(p) == 0) {
;     unsigned* cnt = (unsigned*)(p.ws + OFF_CNT) + 32;
;     __builtin_amdgcn_fence(__ATOMIC_RELEASE, "agent");
;     asm volatile("s_waitcnt vmcnt(0)" ::: "memory");
;     __hip_atomic_fetch_add(cnt, 1u, __ATOMIC_RELAXED, __HIP_MEMORY_SCOPE_AGENT);
;     unsigned spins = 0;
;     while (__hip_atomic_load(cnt, __ATOMIC_RELAXED, __HIP_MEMORY_SCOPE_AGENT) < target) {
;       __builtin_amdgcn_s_sleep(2);
;       if (++spins > (1u << 26)) break;
;     }
;     __builtin_amdgcn_fence(__ATOMIC_ACQUIRE, "agent");
;     asm volatile("s_waitcnt vmcnt(0)" ::: "memory");
;   }
;   __syncthreads();
; }
; __global__ void __launch_bounds__(NTHR) mega(P p0, int ph_lo, int ph_hi) {
;     ...
;   for (int ph = ph_lo; ph < ph_hi; ph++) {
;     if (ph == 0) { if (EN & 1) phase0(p, smem); if (REP0) { grid.sync(); phase0(p, smem); } }
;     else if (ph == 1) { phase1(p); if (REP0) { grid.sync(); phase1(p); } }
;     else if (ph == 2) { phase2(p); if (REP0) { grid.sync(); phase2(p); } }
;     else {
;       const int l = (ph - 3) / 10, i = (ph - 3) % 10;
;       const int nrep = (((REP >> i) & 1) && (i != 5 || l == 0)) ? 2 : 1;
;       for (int rp = 0; rp < nrep; rp++) {
;       if (rp) grid.sync();
.LBB0_1108:
	v_readlane_b32 s1, v255, 9
	s_mov_b32 s3, 0x200
	s_lshr_b32 s3, s3, s1
	s_and_b32 s3, s3, 1
	s_cbranch_scc0 .Lprobe_none
	v_readlane_b32 s2, v255, 61
	s_cmp_ge_u32 s2, 4
	s_cbranch_scc1 .Lprobe_done
	s_add_i32 s2, s2, 1
	v_writelane_b32 v255, s2, 61
	v_readlane_b32 s2, v255, 60
	s_lshl_b32 s3, 1, s1
	s_or_b32 s2, s2, s3
	v_writelane_b32 v255, s2, 60
	v_readlane_b32 s6, v255, 62
	s_add_i32 s6, s6, 1
	v_writelane_b32 v255, s6, 62
	s_mul_i32 s6, s6, s83
	s_waitcnt vmcnt(0) lgkmcnt(0)
	v_sub_u32_e32 v0, 0, v211
	v_readlane_b32 s7, v255, 7
	s_nop 0
	s_barrier
	v_cmp_eq_u32_e32 vcc, s7, v0
	s_and_saveexec_b64 s[4:5], vcc
	s_cbranch_execz .Lprobe_join
	buffer_wbl2 sc1
	s_waitcnt vmcnt(0)
	v_mov_b32_e32 v0, 1
	v_readlane_b32 s2, v254, 42
	v_readlane_b32 s3, v254, 43
	s_nop 4
	global_atomic_add v1, v0, s[2:3] offset:32
.Lprobe_spin:
	global_load_dword v0, v1, s[2:3] offset:32 sc1
	s_waitcnt vmcnt(0)
	v_cmp_le_u32_e32 vcc, s6, v0
	s_cbranch_vccnz .Lprobe_spun
	s_sleep 2
	s_branch .Lprobe_spin

; #define TIDX(p) ((p).wv * 64 + (int)__builtin_amdgcn_mbcnt_hi(~0u, __builtin_amdgcn_mbcnt_lo(~0u, 0u)))
; DI void gbar(const PX& p, unsigned target) {
;   asm volatile("s_waitcnt vmcnt(0)" ::: "memory");
;   __syncthreads();
;   if (TIDX(p) == 0) {
;     unsigned* cnt = (unsigned*)(p.ws + OFF_CNT) + 32;
;     __builtin_amdgcn_fence(__ATOMIC_RELEASE, "agent");
;     asm volatile("s_waitcnt vmcnt(0)" ::: "memory");
;     __hip_atomic_fetch_add(cnt, 1u, __ATOMIC_RELAXED, __HIP_MEMORY_SCOPE_AGENT);
;     unsigned spins = 0;
;     while (__hip_atomic_load(cnt, __ATOMIC_RELAXED, __HIP_MEMORY_SCOPE_AGENT) < target) {
;       __builtin_amdgcn_s_sleep(2);
;       if (++spins > (1u << 26)) break;
;     }
;     __builtin_amdgcn_fence(__ATOMIC_ACQUIRE, "agent");
;     asm volatile("s_waitcnt vmcnt(0)" ::: "memory");
;   }
;   __syncthreads();
; }
; __global__ void __launch_bounds__(NTHR) mega(P p0, int ph_lo, int ph_hi) {
;     ...
;   for (int ph = ph_lo; ph < ph_hi; ph++) {
;     if (ph == 0) { if (EN & 1) phase0(p, smem); if (REP0) { grid.sync(); phase0(p, smem); } }
;     else if (ph == 1) { phase1(p); if (REP0) { grid.sync(); phase1(p); } }
;     else if (ph == 2) { phase2(p); if (REP0) { grid.sync(); phase2(p); } }
;     else {
;       const int l = (ph - 3) / 10, i = (ph - 3) % 10;
;       const int nrep = (((REP >> i) & 1) && (i != 5 || l == 0)) ? 2 : 1;
;       for (int rp = 0; rp < nrep; rp++) {
;       if (rp) grid.sync();
.Lprobe_join:
	s_or_b64 exec, exec, s[4:5]
	s_barrier
	s_mov_b32 s0, s1
	s_mov_b64 s[4:5], 0
	s_branch .LBB0_1123
.Lprobe_done:
	s_mov_b32 s2, 0
	v_writelane_b32 v255, s2, 61
